# stack10: stack8 + removed compiler's vmcnt(0) in the phase-E unit preheader (only stores can be pending there with the hand-written gate epilogue)
# speedup vs baseline: 1.0114x; 1.0114x over previous
.LBB0_1020:
	s_xor_b64 s[52:53], s[54:55], -1
	s_and_b64 s[44:45], s[54:55], exec
	s_cselect_b32 s47, s49, s41
	s_cselect_b32 s54, s48, s40
	s_cselect_b32 s55, s51, s43
	s_cselect_b32 s73, s50, s42
	s_add_i32 s74, s3, -2
	s_add_u32 s40, s40, 0x40080
	s_addc_u32 s41, s41, 0
	s_add_u32 s75, s42, 0x100
	v_mov_b32_e32 v0, 0
	s_addc_u32 s76, s43, 0
	s_mov_b32 s42, 0
	v_mov_b32_e32 v1, v0
	v_mov_b32_e32 v2, v0
	v_mov_b32_e32 v3, v0
	v_mov_b32_e32 v4, v0
	v_mov_b32_e32 v5, v0
	v_mov_b32_e32 v6, v0
	v_mov_b32_e32 v7, v0
	v_mov_b32_e32 v8, v0
	v_mov_b32_e32 v9, v0
	v_mov_b32_e32 v10, v0
	v_mov_b32_e32 v11, v0
	v_mov_b32_e32 v12, v0
	v_mov_b32_e32 v13, v0
	v_mov_b32_e32 v14, v0
	v_mov_b32_e32 v15, v0
	v_mov_b32_e32 v16, v0
	v_mov_b32_e32 v17, v0
	v_mov_b32_e32 v18, v0
	v_mov_b32_e32 v19, v0
	v_mov_b32_e32 v20, v0
	v_mov_b32_e32 v21, v0
	v_mov_b32_e32 v22, v0
	v_mov_b32_e32 v23, v0
	v_mov_b32_e32 v24, v0
	v_mov_b32_e32 v25, v0
	v_mov_b32_e32 v26, v0
	v_mov_b32_e32 v27, v0
	v_mov_b32_e32 v28, v0
	v_mov_b32_e32 v29, v0
	v_mov_b32_e32 v30, v0
	v_mov_b32_e32 v31, v0
	v_mov_b32_e32 v32, v0
	v_mov_b32_e32 v33, v0
	v_mov_b32_e32 v34, v0
	v_mov_b32_e32 v35, v0
	v_mov_b32_e32 v36, v0
	v_mov_b32_e32 v37, v0
	v_mov_b32_e32 v38, v0
	v_mov_b32_e32 v39, v0
	v_mov_b32_e32 v40, v0
	v_mov_b32_e32 v41, v0
	v_mov_b32_e32 v42, v0
	v_mov_b32_e32 v43, v0
	v_mov_b32_e32 v44, v0
	v_mov_b32_e32 v45, v0
	v_mov_b32_e32 v46, v0
	v_mov_b32_e32 v47, v0
	v_mov_b32_e32 v48, v0
	v_mov_b32_e32 v49, v0
	v_mov_b32_e32 v50, v0
	v_mov_b32_e32 v51, v0
	v_mov_b32_e32 v52, v0
	v_mov_b32_e32 v53, v0
	v_mov_b32_e32 v54, v0
	v_mov_b32_e32 v55, v0
	v_mov_b32_e32 v56, v0
	v_mov_b32_e32 v57, v0
	v_mov_b32_e32 v58, v0
	v_mov_b32_e32 v59, v0
	v_mov_b32_e32 v60, v0
	v_mov_b32_e32 v61, v0
	v_mov_b32_e32 v62, v0
	v_mov_b32_e32 v63, v0
	v_mov_b32_e32 v64, v0
	v_mov_b32_e32 v65, v0
	v_mov_b32_e32 v66, v0
	v_mov_b32_e32 v67, v0
	v_mov_b32_e32 v68, v0
	v_mov_b32_e32 v69, v0
	v_mov_b32_e32 v70, v0
	v_mov_b32_e32 v71, v0
	v_mov_b32_e32 v72, v0
	v_mov_b32_e32 v73, v0
	v_mov_b32_e32 v74, v0
	v_mov_b32_e32 v75, v0
	v_mov_b32_e32 v76, v0
	v_mov_b32_e32 v77, v0
	v_mov_b32_e32 v78, v0
	v_mov_b32_e32 v79, v0
	v_mov_b32_e32 v80, v0
	v_mov_b32_e32 v81, v0
	v_mov_b32_e32 v82, v0
	v_mov_b32_e32 v83, v0
	v_mov_b32_e32 v84, v0
	v_mov_b32_e32 v85, v0
	v_mov_b32_e32 v86, v0
	v_mov_b32_e32 v87, v0
	v_mov_b32_e32 v88, v0
	v_mov_b32_e32 v89, v0
	v_mov_b32_e32 v90, v0
	v_mov_b32_e32 v91, v0
	v_mov_b32_e32 v92, v0
	v_mov_b32_e32 v93, v0
	v_mov_b32_e32 v94, v0
	v_mov_b32_e32 v95, v0
	v_mov_b32_e32 v96, v0
	v_mov_b32_e32 v97, v0
	v_mov_b32_e32 v98, v0
	v_mov_b32_e32 v99, v0
	v_mov_b32_e32 v100, v0
	v_mov_b32_e32 v101, v0
	v_mov_b32_e32 v102, v0
	v_mov_b32_e32 v103, v0
	v_mov_b32_e32 v104, v0
	v_mov_b32_e32 v105, v0
	v_mov_b32_e32 v106, v0
	v_mov_b32_e32 v107, v0
	v_mov_b32_e32 v108, v0
	v_mov_b32_e32 v109, v0
	v_mov_b32_e32 v110, v0
	v_mov_b32_e32 v111, v0
	v_mov_b32_e32 v112, v0
	v_mov_b32_e32 v113, v0
	v_mov_b32_e32 v114, v0
	v_mov_b32_e32 v115, v0
	v_mov_b32_e32 v116, v0
	v_mov_b32_e32 v117, v0
	v_mov_b32_e32 v118, v0
	v_mov_b32_e32 v119, v0
	v_mov_b32_e32 v120, v0
	v_mov_b32_e32 v121, v0
	v_mov_b32_e32 v122, v0
	v_mov_b32_e32 v123, v0
	v_mov_b32_e32 v124, v0
	v_mov_b32_e32 v125, v0
	v_mov_b32_e32 v126, v0
	v_mov_b32_e32 v127, v0
